# MLA QK tail: dead multiplies of the replaced masked path removed, V-fragment base computed in the MFMA result wait shadow
# speedup vs baseline: 1.0073x; 1.0073x over previous
; #define LAS __attribute__((address_space(3)))
; DI float ex2(float x) { return __builtin_amdgcn_exp2f(x); }
; DI float max3f(float a, float b, float c) { float r; asm("v_max3_f32 %0, %1, %2, %3" : "=v"(r) : "v"(a), "v"(b), "v"(c)); return r; }
; #define MFMA32(a, b, c) __builtin_amdgcn_mfma_f32_32x32x16_bf16((a), (b), (c), 0, 0, 0)
; template <int MODE>
; DI void attn_unit(LAS unsigned char* lds, const AttnArgs a) {
;     ...
;         for (int ks = 0; ks < NKS; ++ks) {
;             const bf16x8 a0 = *(const LAS bf16x8*)(Kc + r32 * KLD + ks * 16 + 8 * hh);
;             const bf16x8 a1 = *(const LAS bf16x8*)(Kc + (32 + r32) * KLD + ks * 16 + 8 * hh);
;             s0 = MFMA32(a0, qf[ks], s0); s1 = MFMA32(a1, qf[ks], s1);
;         }
;         if (MODE == 2) {
;             if (kbase + 63 < q0w) { sb_block<false>(s1, kbase + 32, qi, hh, a.c2, carry); sb_block<false>(s0, kbase, qi, hh, a.c2, carry); }
;             else                  { sb_block<true>(s1, kbase + 32, qi, hh, a.c2, carry);  sb_block<true>(s0, kbase, qi, hh, a.c2, carry); }
;         } else {
;             const bool interior = (MODE == 0) || (MODE == 1 && kbase + 63 <= q0w);
;             float mnew, alpha, ls = 0.f;
;             if (interior) {
; #pragma unroll
;                 for (int i = 0; i < 16; ++i) { s0[i] *= a.c2; s1[i] *= a.c2; }
;                 float mx = max3f(s0[0], s1[0], s0[1]);
;                 mx = max3f(mx, s1[1], s0[2]); mx = max3f(mx, s1[2], s0[3]); mx = max3f(mx, s1[3], s0[4]); mx = max3f(mx, s1[4], s0[5]);
;                 mx = max3f(mx, s1[5], s0[6]); mx = max3f(mx, s1[6], s0[7]); mx = max3f(mx, s1[7], s0[8]); mx = max3f(mx, s1[8], s0[9]);
;                 mx = max3f(mx, s1[9], s0[10]); mx = max3f(mx, s1[10], s0[11]); mx = max3f(mx, s1[11], s0[12]); mx = max3f(mx, s1[12], s0[13]);
;                 mx = max3f(mx, s1[13], s0[14]); mx = max3f(mx, s1[14], s0[15]); mx = fmaxf(mx, s1[15]);
;                 mx = fmaxf(mx, __shfl_xor(mx, 32));
;                 mnew = fmaxf(mrow, mx); alpha = ex2(mrow - mnew);
.LBB0_156:
	s_mul_i32 s9, s8, 0x2c00
	v_lshl_add_u32 v0, s9, 1, v226
	ds_read_b128 v[2:5], v0
	ds_read_b128 v[6:9], v0 offset:6656
	ds_read_b128 v[10:13], v0 offset:32
	ds_read_b128 v[64:67], v0 offset:6688
	ds_read_b128 v[68:71], v0 offset:64
	ds_read_b128 v[72:75], v0 offset:6720
	ds_read_b128 v[76:79], v0 offset:96
	ds_read_b128 v[154:157], v0 offset:6752
	ds_read_b128 v[158:161], v0 offset:128
	ds_read_b128 v[162:165], v0 offset:6784
	ds_read_b128 v[166:169], v0 offset:160
	ds_read_b128 v[170:173], v0 offset:6816
	s_add_i32 s22, s5, 63
	s_mov_b64 s[6:7], -1
	s_cmp_gt_i32 s22, s19
	s_waitcnt lgkmcnt(11)
	v_mfma_f32_32x32x16_bf16 v[48:63], v[2:5], v[96:99], 0
	s_waitcnt lgkmcnt(10)
	v_mfma_f32_32x32x16_bf16 v[80:95], v[6:9], v[96:99], 0
	s_waitcnt lgkmcnt(9)
	v_mfma_f32_32x32x16_bf16 v[48:63], v[10:13], v[100:103], v[48:63]
	s_waitcnt lgkmcnt(8)
	v_mfma_f32_32x32x16_bf16 v[80:95], v[64:67], v[100:103], v[80:95]
	s_waitcnt lgkmcnt(7)
	v_mfma_f32_32x32x16_bf16 v[48:63], v[68:71], v[104:107], v[48:63]
	s_waitcnt lgkmcnt(6)
	v_mfma_f32_32x32x16_bf16 v[80:95], v[72:75], v[104:107], v[80:95]
	s_waitcnt lgkmcnt(5)
	v_mfma_f32_32x32x16_bf16 v[48:63], v[76:79], v[108:111], v[48:63]
	s_waitcnt lgkmcnt(4)
	v_mfma_f32_32x32x16_bf16 v[80:95], v[154:157], v[108:111], v[80:95]
	s_waitcnt lgkmcnt(3)
	v_mfma_f32_32x32x16_bf16 v[48:63], v[158:161], v[112:115], v[48:63]
	s_waitcnt lgkmcnt(2)
	v_mfma_f32_32x32x16_bf16 v[80:95], v[162:165], v[112:115], v[80:95]
	s_waitcnt lgkmcnt(1)
	v_mfma_f32_32x32x16_bf16 v[48:63], v[166:169], v[116:119], v[48:63]
	s_waitcnt lgkmcnt(0)
	v_mfma_f32_32x32x16_bf16 v[80:95], v[170:173], v[116:119], v[80:95]
	s_mul_i32 s23, s9, 2
	v_add_u32_e32 v158, s23, v200
	v_add_u32_e32 v159, s23, v201
	s_nop 8
	s_cbranch_scc1 .LBB0_182
.Lmla_fused:
	v_max3_f32 v0, v48, v49, v50
	v_max3_f32 v14, v80, v81, v82
	v_max3_f32 v0, v0, v51, v52
	v_max3_f32 v14, v14, v83, v84
	v_max3_f32 v0, v0, v53, v54
	v_max3_f32 v14, v14, v85, v86
	v_max3_f32 v0, v0, v55, v56
	v_max3_f32 v14, v14, v87, v88
	v_max3_f32 v0, v0, v57, v58
	v_max3_f32 v14, v14, v89, v90
	v_max3_f32 v0, v0, v59, v60
	v_max3_f32 v14, v14, v91, v92
	v_max3_f32 v0, v0, v61, v62
	v_max3_f32 v14, v14, v93, v94
	v_max3_f32 v0, v0, v63, v14
	v_max_f32_e32 v0, v0, v95
	s_mov_b32 s6, 0x3e16c740
	v_mul_f32_e32 v0, 0x3e16c740, v0
	v_mov_b32_e32 v3, v0
	s_nop 1
	v_permlane32_swap_b32 v0, v3
	ds_read_b64_tr_b16 v[64:65], v158 offset:13568
	ds_read_b64_tr_b16 v[66:67], v158 offset:14592
	ds_read_b64_tr_b16 v[68:69], v159 offset:13568
	ds_read_b64_tr_b16 v[70:71], v159 offset:14592
	ds_read_b64_tr_b16 v[72:73], v158 offset:15616
	ds_read_b64_tr_b16 v[74:75], v158 offset:16640
	ds_read_b64_tr_b16 v[76:77], v159 offset:15616
	ds_read_b64_tr_b16 v[78:79], v159 offset:16640
	v_max3_f32 v231, v232, v0, v3
	v_sub_f32_e32 v2, v232, v231
	v_exp_f32_e32 v2, v2
	v_fma_f32 v48, v48, s6, -v231
	v_fma_f32 v49, v49, s6, -v231
	v_fma_f32 v50, v50, s6, -v231
	v_fma_f32 v51, v51, s6, -v231
	v_fma_f32 v52, v52, s6, -v231
	v_fma_f32 v53, v53, s6, -v231
	v_fma_f32 v54, v54, s6, -v231
	v_fma_f32 v55, v55, s6, -v231
	v_cmp_gt_f32_e32 vcc, 1.0, v2
	s_cbranch_vccz .Lmla_f_nors
	v_pk_mul_f32 v[46:47], v[46:47], v[2:3] op_sel_hi:[1,0]
	v_pk_mul_f32 v[44:45], v[44:45], v[2:3] op_sel_hi:[1,0]
	v_pk_mul_f32 v[42:43], v[42:43], v[2:3] op_sel_hi:[1,0]
	v_pk_mul_f32 v[40:41], v[40:41], v[2:3] op_sel_hi:[1,0]
	v_pk_mul_f32 v[38:39], v[38:39], v[2:3] op_sel_hi:[1,0]
	v_pk_mul_f32 v[36:37], v[36:37], v[2:3] op_sel_hi:[1,0]
	v_pk_mul_f32 v[34:35], v[34:35], v[2:3] op_sel_hi:[1,0]
	v_pk_mul_f32 v[32:33], v[32:33], v[2:3] op_sel_hi:[1,0]
	v_pk_mul_f32 v[30:31], v[30:31], v[2:3] op_sel_hi:[1,0]
	v_pk_mul_f32 v[28:29], v[28:29], v[2:3] op_sel_hi:[1,0]
	v_pk_mul_f32 v[26:27], v[26:27], v[2:3] op_sel_hi:[1,0]
	v_pk_mul_f32 v[24:25], v[24:25], v[2:3] op_sel_hi:[1,0]
	v_pk_mul_f32 v[22:23], v[22:23], v[2:3] op_sel_hi:[1,0]
	v_pk_mul_f32 v[20:21], v[20:21], v[2:3] op_sel_hi:[1,0]
	v_pk_mul_f32 v[18:19], v[18:19], v[2:3] op_sel_hi:[1,0]
	v_pk_mul_f32 v[16:17], v[16:17], v[2:3] op_sel_hi:[1,0]
